# v46 + dilated attention QK^T: K-fragment ds_reads issued 3-4 MFMAs ahead using spare VGPR quads (counted lgkmcnt)
# baseline (speedup 1.0000x reference)
; #define SBAR() __builtin_amdgcn_sched_barrier(0)
; #define ACT(t) (KBASE(t) <= qlo + QBLK - 1 && KBASE(t) + KVBLK - 1 >= qlo - W + 1)
; template <int KB, bool SK, bool PE>
; __device__ __forceinline__ void qkt(f32x16& p0, f32x16& p1, const char* lds, int r32, int hi, int wid, int lane, const bf16x8* qr, bool act) {
;     ...
;     p0 = f32x16{}; p1 = f32x16{};
;     const char* kb[4];
; #pragma unroll
;     for (int dd = 0; dd < 4; ++dd) kb[dd] = lds + OFF_K + KB * SHM_K + KSWZ(r32, (dd * 16 + hi * 8) * 2);
; #pragma unroll
;     for (int d0 = 0; d0 < 8; ++d0) { const char* a = kb[d0 & 3] + (d0 >> 2) * 128;
;         bf16x8 b0 = *reinterpret_cast<const bf16x8*>(a);
;         bf16x8 b1 = *reinterpret_cast<const bf16x8*>(a + 32 * 256);
;         p0 = __builtin_amdgcn_mfma_f32_32x32x16_bf16(b0, qr[d0], p0, 0, 0, 0);
;         p1 = __builtin_amdgcn_mfma_f32_32x32x16_bf16(b1, qr[d0], p1, 0, 0, 0); }
; template <bool PE, bool SK, bool LSE, bool EARLY>
; __device__ __forceinline__ void swa_block(const BlockRef& cur, const BlockRef& nxt, const Prm& P, char* lds, Seam<PE>& S) {
;     ...
;     SBAR(); qkt<0, SK, PE>(pA0, pA1, lds, r32, hi, wid, lane, S.qr, ACT(0));
.LBB0_824:
	s_ashr_i32 s52, s9, 1
	s_andn2_b32 s52, s52, 31
	v_and_b32_e32 v213, 31, v50
	v_bfe_u32 v53, v50, 5, 1
	s_add_i32 s20, s52, s8
	s_lshl_b32 s13, s12, 6
	s_or_b32 s21, s20, 31
	s_cmp_gt_i32 s13, s21
	s_cselect_b64 s[8:9], -1, 0
	s_or_b32 s24, s13, 63
	s_add_i32 s42, s20, 0xffffff7f
	s_cmp_le_i32 s24, s42
	s_cselect_b64 s[54:55], -1, 0
	s_or_b64 s[8:9], s[8:9], s[54:55]
	s_and_b64 vcc, exec, s[8:9]
	v_lshlrev_b32_e32 v214, 4, v53
	s_cbranch_vccnz .LBB0_826
	v_lshlrev_b32_e32 v8, 4, v213
	v_lshlrev_b32_e32 v3, 8, v213
	v_bitop3_b32 v4, v214, v8, s93 bitop3:0x78
	v_add3_u32 v9, 0, v4, v3
	ds_read_b128 v[4:7], v9 offset:32768
	v_and_b32_e32 v8, 0x70, v8
	v_bitop3_b32 v10, v214, v8, 32 bitop3:0x36
	v_add3_u32 v10, 0, v10, v3
	v_bitop3_b32 v11, v214, v8, 64 bitop3:0x36
	v_add3_u32 v11, 0, v11, v3
	v_bitop3_b32 v8, v214, v8, s16 bitop3:0x36
	v_add3_u32 v3, 0, v8, v3
	ds_read_b128 v[244:247], v9 offset:40960
	ds_read_b128 v[248:251], v10 offset:32768
	s_waitcnt vmcnt(15) lgkmcnt(2)
	v_mfma_f32_32x32x16_bf16 v[34:49], v[4:7], v[166:169], 0
	ds_read_b128 v[4:7], v10 offset:40960
	s_waitcnt lgkmcnt(2)
	v_mfma_f32_32x32x16_bf16 v[18:33], v[244:247], v[166:169], 0
	ds_read_b128 v[244:247], v11 offset:32768
	s_waitcnt vmcnt(14) lgkmcnt(2)
	v_mfma_f32_32x32x16_bf16 v[34:49], v[248:251], v[162:165], v[34:49]
	ds_read_b128 v[248:251], v11 offset:40960
	s_waitcnt lgkmcnt(2)
	v_mfma_f32_32x32x16_bf16 v[18:33], v[4:7], v[162:165], v[18:33]
	ds_read_b128 v[4:7], v3 offset:32768
	s_waitcnt vmcnt(5) lgkmcnt(2)
	v_mfma_f32_32x32x16_bf16 v[34:49], v[244:247], v[174:177], v[34:49]
	ds_read_b128 v[244:247], v3 offset:40960
	s_waitcnt lgkmcnt(2)
	v_mfma_f32_32x32x16_bf16 v[18:33], v[248:251], v[174:177], v[18:33]
	ds_read_b128 v[248:251], v9 offset:32896
	s_waitcnt vmcnt(4) lgkmcnt(2)
	v_mfma_f32_32x32x16_bf16 v[34:49], v[4:7], v[170:173], v[34:49]
	ds_read_b128 v[4:7], v9 offset:41088
	s_waitcnt lgkmcnt(2)
	v_mfma_f32_32x32x16_bf16 v[18:33], v[244:247], v[170:173], v[18:33]
	ds_read_b128 v[244:247], v10 offset:32896
	s_waitcnt vmcnt(3) lgkmcnt(2)
	v_mfma_f32_32x32x16_bf16 v[34:49], v[248:251], v[158:161], v[34:49]
	ds_read_b128 v[248:251], v10 offset:41088
	s_waitcnt lgkmcnt(2)
	v_mfma_f32_32x32x16_bf16 v[18:33], v[4:7], v[158:161], v[18:33]
	ds_read_b128 v[4:7], v11 offset:32896
	s_waitcnt vmcnt(2) lgkmcnt(2)
	v_mfma_f32_32x32x16_bf16 v[34:49], v[244:247], v[154:157], v[34:49]
	ds_read_b128 v[244:247], v11 offset:41088
	s_waitcnt lgkmcnt(2)
	v_mfma_f32_32x32x16_bf16 v[18:33], v[248:251], v[154:157], v[18:33]
	ds_read_b128 v[248:251], v3 offset:32896
	s_waitcnt vmcnt(1) lgkmcnt(2)
	v_mfma_f32_32x32x16_bf16 v[34:49], v[4:7], v[150:153], v[34:49]
	ds_read_b128 v[4:7], v3 offset:41088
	s_waitcnt lgkmcnt(2)
	v_mfma_f32_32x32x16_bf16 v[18:33], v[244:247], v[150:153], v[18:33]
	s_waitcnt vmcnt(0) lgkmcnt(1)
	v_mfma_f32_32x32x16_bf16 v[34:49], v[248:251], v[146:149], v[34:49]
	s_waitcnt lgkmcnt(0)
	v_mfma_f32_32x32x16_bf16 v[18:33], v[4:7], v[146:149], v[18:33]
	s_branch .LBB0_827

; template <int KB, bool SK, bool PE>
; __device__ __forceinline__ void qkt(f32x16& p0, f32x16& p1, const char* lds, int r32, int hi, int wid, int lane, const bf16x8* qr, bool act) {
;     ...
;     for (int dd = 0; dd < 4; ++dd) kb[dd] = lds + OFF_K + KB * SHM_K + KSWZ(r32, (dd * 16 + hi * 8) * 2);
; #pragma unroll
;     for (int d0 = 0; d0 < 8; ++d0) { const char* a = kb[d0 & 3] + (d0 >> 2) * 128;
;         bf16x8 b0 = *reinterpret_cast<const bf16x8*>(a);
;         bf16x8 b1 = *reinterpret_cast<const bf16x8*>(a + 32 * 256);
;         p0 = __builtin_amdgcn_mfma_f32_32x32x16_bf16(b0, qr[d0], p0, 0, 0, 0);
;         p1 = __builtin_amdgcn_mfma_f32_32x32x16_bf16(b1, qr[d0], p1, 0, 0, 0); }
.LBB0_835:
	s_sub_i32 s44, s54, 63
	s_lshl_b64 s[8:9], s[44:45], 8
	s_add_u32 s10, s90, s8
	s_addc_u32 s11, s91, s9
	s_add_u32 s8, s94, s8
	s_addc_u32 s9, s95, s9
	v_lshl_add_u64 v[4:5], s[8:9], 0, v[200:201]
	v_add_co_u32_e32 v6, vcc, s43, v4
	s_nop 1
	v_addc_co_u32_e32 v7, vcc, 0, v5, vcc
	global_load_dwordx4 v[178:181], v[4:5], off
	global_load_dwordx4 v[182:185], v[6:7], off
	v_lshl_add_u64 v[4:5], s[10:11], 0, v[200:201]
	v_add_co_u32_e32 v6, vcc, 0x2000, v4
	s_nop 1
	v_addc_co_u32_e32 v7, vcc, 0, v5, vcc
	global_load_dwordx4 v[186:189], v[4:5], off
	global_load_dwordx4 v[190:193], v[6:7], off
	s_add_i32 s10, s54, 0xffffff81
	s_cmp_gt_i32 s10, s21
	s_cselect_b64 s[8:9], -1, 0
	s_sub_i32 s11, s54, 64
	s_cmp_le_i32 s11, s42
	s_cselect_b64 s[12:13], -1, 0
	s_or_b64 s[8:9], s[8:9], s[12:13]
	s_and_b64 vcc, exec, s[8:9]
	s_cbranch_vccnz .LBB0_837
	ds_read_b128 v[4:7], v218 offset:49152
	ds_read_b128 v[244:247], v218 offset:57344
	ds_read_b128 v[248:251], v219 offset:49152
	s_waitcnt vmcnt(19) lgkmcnt(2)
	v_mfma_f32_32x32x16_bf16 v[98:113], v[4:7], v[166:169], 0
	ds_read_b128 v[4:7], v219 offset:57344
	s_waitcnt lgkmcnt(2)
	v_mfma_f32_32x32x16_bf16 v[82:97], v[244:247], v[166:169], 0
	ds_read_b128 v[244:247], v220 offset:49152
	s_waitcnt vmcnt(18) lgkmcnt(2)
	v_mfma_f32_32x32x16_bf16 v[98:113], v[248:251], v[162:165], v[98:113]
	ds_read_b128 v[248:251], v220 offset:57344
	s_waitcnt lgkmcnt(2)
	v_mfma_f32_32x32x16_bf16 v[82:97], v[4:7], v[162:165], v[82:97]
	ds_read_b128 v[4:7], v221 offset:49152
	s_waitcnt vmcnt(9) lgkmcnt(2)
	v_mfma_f32_32x32x16_bf16 v[98:113], v[244:247], v[174:177], v[98:113]
	ds_read_b128 v[244:247], v221 offset:57344
	s_waitcnt lgkmcnt(2)
	v_mfma_f32_32x32x16_bf16 v[82:97], v[248:251], v[174:177], v[82:97]
	ds_read_b128 v[248:251], v218 offset:49280
	s_waitcnt vmcnt(8) lgkmcnt(2)
	v_mfma_f32_32x32x16_bf16 v[98:113], v[4:7], v[170:173], v[98:113]
	ds_read_b128 v[4:7], v218 offset:57472
	s_waitcnt lgkmcnt(2)
	v_mfma_f32_32x32x16_bf16 v[82:97], v[244:247], v[170:173], v[82:97]
	ds_read_b128 v[244:247], v219 offset:49280
	s_waitcnt vmcnt(7) lgkmcnt(2)
	v_mfma_f32_32x32x16_bf16 v[98:113], v[248:251], v[158:161], v[98:113]
	ds_read_b128 v[248:251], v219 offset:57472
	s_waitcnt lgkmcnt(2)
	v_mfma_f32_32x32x16_bf16 v[82:97], v[4:7], v[158:161], v[82:97]
	ds_read_b128 v[4:7], v220 offset:49280
	s_waitcnt vmcnt(6) lgkmcnt(2)
	v_mfma_f32_32x32x16_bf16 v[98:113], v[244:247], v[154:157], v[98:113]
	ds_read_b128 v[244:247], v220 offset:57472
	s_waitcnt lgkmcnt(2)
	v_mfma_f32_32x32x16_bf16 v[82:97], v[248:251], v[154:157], v[82:97]
	ds_read_b128 v[248:251], v221 offset:49280
	s_waitcnt vmcnt(5) lgkmcnt(2)
	v_mfma_f32_32x32x16_bf16 v[98:113], v[4:7], v[150:153], v[98:113]
	ds_read_b128 v[4:7], v221 offset:57472
	s_waitcnt lgkmcnt(2)
	v_mfma_f32_32x32x16_bf16 v[82:97], v[244:247], v[150:153], v[82:97]
	s_waitcnt vmcnt(4) lgkmcnt(1)
	v_mfma_f32_32x32x16_bf16 v[98:113], v[248:251], v[146:149], v[98:113]
	s_waitcnt lgkmcnt(0)
	v_mfma_f32_32x32x16_bf16 v[82:97], v[4:7], v[146:149], v[82:97]
	s_branch .LBB0_838

; template <int KB, bool SK, bool PE>
; __device__ __forceinline__ void qkt(f32x16& p0, f32x16& p1, const char* lds, int r32, int hi, int wid, int lane, const bf16x8* qr, bool act) {
;     ...
;     for (int dd = 0; dd < 4; ++dd) kb[dd] = lds + OFF_K + KB * SHM_K + KSWZ(r32, (dd * 16 + hi * 8) * 2);
; #pragma unroll
;     for (int d0 = 0; d0 < 8; ++d0) { const char* a = kb[d0 & 3] + (d0 >> 2) * 128;
;         bf16x8 b0 = *reinterpret_cast<const bf16x8*>(a);
;         bf16x8 b1 = *reinterpret_cast<const bf16x8*>(a + 32 * 256);
;         p0 = __builtin_amdgcn_mfma_f32_32x32x16_bf16(b0, qr[d0], p0, 0, 0, 0);
;         p1 = __builtin_amdgcn_mfma_f32_32x32x16_bf16(b1, qr[d0], p1, 0, 0, 0); }
.LBB0_847:
	s_cmp_gt_i32 s44, s21
	s_cselect_b64 s[48:49], -1, 0
	s_cmp_le_i32 s54, s42
	s_cselect_b64 s[68:69], -1, 0
	s_or_b64 s[68:69], s[48:49], s[68:69]
	s_and_b64 vcc, exec, s[68:69]
	s_cbranch_vccnz .LBB0_849
	ds_read_b128 v[4:7], v218 offset:32768
	ds_read_b128 v[244:247], v218 offset:40960
	ds_read_b128 v[248:251], v219 offset:32768
	s_waitcnt lgkmcnt(2)
	v_mfma_f32_32x32x16_bf16 v[130:145], v[4:7], v[166:169], 0
	ds_read_b128 v[4:7], v219 offset:40960
	s_waitcnt lgkmcnt(2)
	v_mfma_f32_32x32x16_bf16 v[114:129], v[244:247], v[166:169], 0
	ds_read_b128 v[244:247], v220 offset:32768
	s_waitcnt lgkmcnt(2)
	v_mfma_f32_32x32x16_bf16 v[130:145], v[248:251], v[162:165], v[130:145]
	ds_read_b128 v[248:251], v220 offset:40960
	s_waitcnt lgkmcnt(2)
	v_mfma_f32_32x32x16_bf16 v[114:129], v[4:7], v[162:165], v[114:129]
	ds_read_b128 v[4:7], v221 offset:32768
	s_waitcnt lgkmcnt(2)
	v_mfma_f32_32x32x16_bf16 v[130:145], v[244:247], v[174:177], v[130:145]
	ds_read_b128 v[244:247], v221 offset:40960
	s_waitcnt lgkmcnt(2)
	v_mfma_f32_32x32x16_bf16 v[114:129], v[248:251], v[174:177], v[114:129]
	ds_read_b128 v[248:251], v218 offset:32896
	s_waitcnt lgkmcnt(2)
	v_mfma_f32_32x32x16_bf16 v[130:145], v[4:7], v[170:173], v[130:145]
	ds_read_b128 v[4:7], v218 offset:41088
	s_waitcnt lgkmcnt(2)
	v_mfma_f32_32x32x16_bf16 v[114:129], v[244:247], v[170:173], v[114:129]
	ds_read_b128 v[244:247], v219 offset:32896
	s_waitcnt lgkmcnt(2)
	v_mfma_f32_32x32x16_bf16 v[130:145], v[248:251], v[158:161], v[130:145]
	ds_read_b128 v[248:251], v219 offset:41088
	s_waitcnt lgkmcnt(2)
	v_mfma_f32_32x32x16_bf16 v[114:129], v[4:7], v[158:161], v[114:129]
	ds_read_b128 v[4:7], v220 offset:32896
	s_waitcnt lgkmcnt(2)
	v_mfma_f32_32x32x16_bf16 v[130:145], v[244:247], v[154:157], v[130:145]
	ds_read_b128 v[244:247], v220 offset:41088
	s_waitcnt lgkmcnt(2)
	v_mfma_f32_32x32x16_bf16 v[114:129], v[248:251], v[154:157], v[114:129]
	ds_read_b128 v[248:251], v221 offset:32896
	s_waitcnt lgkmcnt(2)
	v_mfma_f32_32x32x16_bf16 v[130:145], v[4:7], v[150:153], v[130:145]
	ds_read_b128 v[4:7], v221 offset:41088
	s_waitcnt lgkmcnt(2)
	v_mfma_f32_32x32x16_bf16 v[114:129], v[244:247], v[150:153], v[114:129]
	s_waitcnt lgkmcnt(1)
	v_mfma_f32_32x32x16_bf16 v[130:145], v[248:251], v[146:149], v[130:145]
	s_waitcnt lgkmcnt(0)
	v_mfma_f32_32x32x16_bf16 v[114:129], v[4:7], v[146:149], v[114:129]
	s_branch .LBB0_850

; #define SBAR() __builtin_amdgcn_sched_barrier(0)
; #define ACT(t) (KBASE(t) <= qlo + QBLK - 1 && KBASE(t) + KVBLK - 1 >= qlo - W + 1)
; template <int KB, bool SK, bool PE>
; __device__ __forceinline__ void qkt(f32x16& p0, f32x16& p1, const char* lds, int r32, int hi, int wid, int lane, const bf16x8* qr, bool act) {
;     ...
;     p0 = f32x16{}; p1 = f32x16{};
;     const char* kb[4];
; #pragma unroll
;     for (int dd = 0; dd < 4; ++dd) kb[dd] = lds + OFF_K + KB * SHM_K + KSWZ(r32, (dd * 16 + hi * 8) * 2);
; #pragma unroll
;     for (int d0 = 0; d0 < 8; ++d0) { const char* a = kb[d0 & 3] + (d0 >> 2) * 128;
;         bf16x8 b0 = *reinterpret_cast<const bf16x8*>(a);
;         bf16x8 b1 = *reinterpret_cast<const bf16x8*>(a + 32 * 256);
;         p0 = __builtin_amdgcn_mfma_f32_32x32x16_bf16(b0, qr[d0], p0, 0, 0, 0);
;         p1 = __builtin_amdgcn_mfma_f32_32x32x16_bf16(b1, qr[d0], p1, 0, 0, 0); }
; template <bool PE, bool SK, bool LSE, bool EARLY>
; __device__ __forceinline__ void swa_block(const BlockRef& cur, const BlockRef& nxt, const Prm& P, char* lds, Seam<PE>& S) {
;     ...
;     if (even) { SBAR(); qkt<1, SK, PE>(pB0, pB1, lds, r32, hi, wid, lane, S.qr, ACT(NT - 1)); SBAR(); }
.LBB0_860:
	s_bitcmp0_b32 s23, 0
	s_cselect_b64 s[8:9], -1, 0
	s_and_b64 vcc, exec, s[8:9]
	s_cbranch_vccz .LBB0_865
	s_lshl_b32 s12, s1, 6
	s_sub_i32 s10, s12, 64
	s_cmp_le_i32 s10, s21
	s_cselect_b64 s[10:11], -1, 0
	s_add_i32 s13, s20, 0xffffff80
	s_cmp_gt_i32 s12, s13
	s_cselect_b64 s[12:13], -1, 0
	s_and_b64 s[10:11], s[10:11], s[12:13]
	s_andn2_b64 vcc, exec, s[10:11]
	s_cbranch_vccnz .LBB0_863
	v_lshlrev_b32_e32 v4, 4, v213
	v_lshlrev_b32_e32 v3, 8, v213
	v_and_b32_e32 v5, 0x70, v4
	v_bitop3_b32 v4, v214, v4, s93 bitop3:0x78
	v_add3_u32 v12, 0, v4, v3
	v_bitop3_b32 v4, v214, v5, 32 bitop3:0x36
	v_add3_u32 v13, 0, v4, v3
	v_bitop3_b32 v4, v214, v5, 64 bitop3:0x36
	v_add3_u32 v14, 0, v4, v3
	v_bitop3_b32 v4, v214, v5, s16 bitop3:0x36
	v_add3_u32 v3, 0, v4, v3
	ds_read_b128 v[4:7], v12 offset:49152
	ds_read_b128 v[8:11], v12 offset:57344
	ds_read_b128 v[244:247], v13 offset:49152
	ds_read_b128 v[248:251], v13 offset:57344
	s_waitcnt vmcnt(15) lgkmcnt(3)
	v_mfma_f32_32x32x16_bf16 v[82:97], v[4:7], v[166:169], 0
	ds_read_b128 v[4:7], v14 offset:49152
	s_waitcnt lgkmcnt(3)
	v_mfma_f32_32x32x16_bf16 v[98:113], v[8:11], v[166:169], 0
	ds_read_b128 v[8:11], v14 offset:57344
	s_waitcnt vmcnt(14) lgkmcnt(3)
	v_mfma_f32_32x32x16_bf16 v[82:97], v[244:247], v[162:165], v[82:97]
	ds_read_b128 v[244:247], v3 offset:49152
	s_waitcnt lgkmcnt(3)
	v_mfma_f32_32x32x16_bf16 v[98:113], v[248:251], v[162:165], v[98:113]
	ds_read_b128 v[248:251], v3 offset:57344
	s_waitcnt vmcnt(5) lgkmcnt(3)
	v_mfma_f32_32x32x16_bf16 v[82:97], v[4:7], v[174:177], v[82:97]
	ds_read_b128 v[4:7], v12 offset:49280
	s_waitcnt lgkmcnt(3)
	v_mfma_f32_32x32x16_bf16 v[98:113], v[8:11], v[174:177], v[98:113]
	ds_read_b128 v[8:11], v12 offset:57472
	s_waitcnt vmcnt(4) lgkmcnt(3)
	v_mfma_f32_32x32x16_bf16 v[82:97], v[244:247], v[170:173], v[82:97]
	ds_read_b128 v[244:247], v13 offset:49280
	s_waitcnt lgkmcnt(3)
	v_mfma_f32_32x32x16_bf16 v[98:113], v[248:251], v[170:173], v[98:113]
	ds_read_b128 v[248:251], v13 offset:57472
	s_waitcnt vmcnt(3) lgkmcnt(3)
	v_mfma_f32_32x32x16_bf16 v[82:97], v[4:7], v[158:161], v[82:97]
	ds_read_b128 v[4:7], v14 offset:49280
	s_waitcnt lgkmcnt(3)
	v_mfma_f32_32x32x16_bf16 v[98:113], v[8:11], v[158:161], v[98:113]
	ds_read_b128 v[8:11], v14 offset:57472
	s_waitcnt vmcnt(2) lgkmcnt(3)
	v_mfma_f32_32x32x16_bf16 v[82:97], v[244:247], v[154:157], v[82:97]
	ds_read_b128 v[244:247], v3 offset:49280
	s_waitcnt lgkmcnt(3)
	v_mfma_f32_32x32x16_bf16 v[98:113], v[248:251], v[154:157], v[98:113]
	ds_read_b128 v[248:251], v3 offset:57472
	s_waitcnt vmcnt(1) lgkmcnt(3)
	v_mfma_f32_32x32x16_bf16 v[82:97], v[4:7], v[150:153], v[82:97]
	s_waitcnt lgkmcnt(2)
	v_mfma_f32_32x32x16_bf16 v[98:113], v[8:11], v[150:153], v[98:113]
	s_waitcnt vmcnt(0) lgkmcnt(1)
	v_mfma_f32_32x32x16_bf16 v[82:97], v[244:247], v[146:149], v[82:97]
	s_waitcnt lgkmcnt(0)
	v_mfma_f32_32x32x16_bf16 v[98:113], v[248:251], v[146:149], v[98:113]
	s_branch .LBB0_864
